# w_in GEMM: row-rstd table computed inside the last K iteration (2 threads per row + DPP combine), epilogue stage_rstd removed
# speedup vs baseline: 1.0207x; 1.0046x over previous
; __device__ __forceinline__ float sum4(const f32x4 a) { return (a[0] + a[1]) + (a[2] + a[3]); }
; #define PG8_STAGE(bufoff, gbase, voff) do { _Pragma("unroll") for (int _i = 0; _i < 2; ++_i) \
;         __builtin_amdgcn_global_load_lds((const unsigned*)((const char*)(gbase) + (voff)[_i]), (PG8_LAS unsigned*)(lds + (bufoff) + ldsw + _i * 8192), 16, 0, 0); } while (0)
; #define PG8_LDA(dst, b, h) do { _Pragma("unroll") for (int m = 0; m < 4; ++m) _Pragma("unroll") for (int k = 0; k < 2; ++k) dst[m][k] = *(const PG8_LAS bf16x8*)(lds + PG8_SA(b, h) + aoff + m * 2048 + k * 1024); } while (0)
; #define PG8_LDB(dst, b, h) do { _Pragma("unroll") for (int n = 0; n < 2; ++n) _Pragma("unroll") for (int k = 0; k < 2; ++k) dst[n][k] = *(const PG8_LAS bf16x8*)(lds + PG8_SB(b, h) + boff + n * 2048 + k * 1024); } while (0)
; #define PG8_MMA(ai, bj, At, Bt) do { __builtin_amdgcn_s_setprio(1); _Pragma("unroll") for (int m = 0; m < 4; ++m) _Pragma("unroll") for (int n = 0; n < 2; ++n) _Pragma("unroll") for (int k = 0; k < 2; ++k) \
;         acc[ai][bj][m][n] = __builtin_amdgcn_mfma_f32_16x16x32_bf16(Bt[n][k], At[m][k], acc[ai][bj][m][n], 0, 0, 0); __builtin_amdgcn_s_setprio(0); } while (0)
; #define PG8_WAIT_V(n) asm volatile("s_waitcnt vmcnt(" #n ")" ::: "memory")
; __device__ __forceinline__ float row_rstd(const float* ps_row) {
;     const f32x4* p = (const f32x4*)ps_row; const f32x4 a = p[0], b = p[1], c = p[2], d = p[3];
;     const float s = (sum4(a) + sum4(b)) + (sum4(c) + sum4(d));
; template <class Epi, class Sched, bool ALIGN_EPI = false, bool SP2 = false>
; __device__ __forceinline__ void gemm_phase(PG8_LAS unsigned char* lds, const Gemm g, const Sched& S, const Epi& E) {
;     ...
;         for (int t = 0; t < nt; t += 2) {
;             const bool last = (t == nt - 2);
;             const char* a1 = cA + (size_t)(t + 1) * kstep;
;             const char* a2 = last ? nA : cA + (size_t)(t + 2) * kstep; const char* b2 = last ? nB : cB + (size_t)(t + 2) * kstep;
;             const char* a3 = a2 + kstep; const char* b3 = b2 + kstep;
;             if (last && has_next) S.a_ready(nxt);
;             if constexpr (SP2) {
;             PG8_LDB(B0, 0, 0); PG8_LDB(B1, 0, 1); PG8_SCHED; PG8_LDA(At, 0, 0); PG8_STAGE(PG8_SA(1, 1), a1 + hstep, voffA);
;             PG8_WAIT_V(8); PG8_WAIT_L(0); PG8_BAR; PG8_MMA(0, 0, At, B0); PG8_MMA(0, 1, At, B1); PG8_BAR; PG8_SCHED;
.LBB0_533:
	s_add_u32 s2, s0, 0xfffc0080
	s_addc_u32 s3, s1, -1
	s_add_i32 s39, 0, 0x10000
	s_cmp_eq_u32 s38, 12
	s_cselect_b32 s25, s4, s3
	s_cselect_b32 s24, s5, s2
	s_cselect_b32 s3, s6, s19
	s_cselect_b32 s2, s7, s11
	s_cmp_eq_u32 s38, 12
	s_cbranch_scc0 .Lrs_in_a
	s_lshl_b32 s98, s53, 8
	v_lshrrev_b32_e32 v250, 1, v216
	v_add_u32_e32 v250, s98, v250
	v_and_b32_e32 v217, 1, v216
	v_lshlrev_b32_e32 v217, 5, v217
	v_lshl_add_u32 v250, v250, 6, v217
	global_load_dwordx2 v[190:191], v250, s[56:57]
	global_load_dwordx2 v[226:227], v250, s[56:57] offset:8
	global_load_dword v217, v250, s[56:57] offset:16
	global_load_dword v220, v250, s[56:57] offset:20
	global_load_dword v223, v250, s[56:57] offset:24
	global_load_dword v250, v250, s[56:57] offset:28
.Lrs_in_a:
	s_add_i32 s54, 0, 0x14000
	v_add_u32_e32 v140, s39, v155
	v_add_u32_e32 v184, s54, v155
	ds_read_b128 v[128:131], v140
	ds_read_b128 v[132:135], v140 offset:1024
	ds_read_b128 v[136:139], v140 offset:2048
	ds_read_b128 v[140:143], v140 offset:3072
	ds_read_b128 v[170:173], v184
	ds_read_b128 v[174:177], v184 offset:1024
	ds_read_b128 v[180:183], v184 offset:2048
	ds_read_b128 v[194:197], v184 offset:3072
	v_lshl_add_u64 v[214:215], s[0:1], 0, v[166:167]
	s_add_i32 m0, s23, 0xc000
	ds_read_b128 v[198:201], v179
	ds_read_b128 v[202:205], v179 offset:1024
	ds_read_b128 v[206:209], v179 offset:2048
	ds_read_b128 v[210:213], v179 offset:3072
	ds_read_b128 v[228:231], v179 offset:4096
	ds_read_b128 v[232:235], v179 offset:5120
	ds_read_b128 v[236:239], v179 offset:6144
	ds_read_b128 v[240:243], v179 offset:7168
	global_load_lds_dwordx4 v[214:215], off
	v_lshl_add_u64 v[214:215], s[0:1], 0, v[168:169]
	s_add_i32 m0, s23, 0xe000
	s_nop 0
	global_load_lds_dwordx4 v[214:215], off
	s_waitcnt vmcnt(8)
	s_waitcnt lgkmcnt(0)
	s_barrier
	s_setprio 1
	s_waitcnt lgkmcnt(0)
	v_mfma_f32_16x16x32_bf16 v[124:127], v[128:131], v[198:201], v[124:127]
	v_mfma_f32_16x16x32_bf16 v[120:123], v[136:139], v[198:201], v[120:123]
	v_mfma_f32_16x16x32_bf16 v[108:111], v[128:131], v[206:209], v[108:111]
	v_mfma_f32_16x16x32_bf16 v[104:107], v[136:139], v[206:209], v[104:107]
	v_mfma_f32_16x16x32_bf16 v[92:95], v[128:131], v[228:231], v[92:95]
	v_mfma_f32_16x16x32_bf16 v[88:91], v[136:139], v[228:231], v[88:91]
	v_mfma_f32_16x16x32_bf16 v[76:79], v[128:131], v[236:239], v[76:79]
	v_mfma_f32_16x16x32_bf16 v[72:75], v[136:139], v[236:239], v[72:75]
	v_mfma_f32_16x16x32_bf16 v[124:127], v[132:135], v[202:205], v[124:127]
	v_mfma_f32_16x16x32_bf16 v[120:123], v[140:143], v[202:205], v[120:123]
	v_mfma_f32_16x16x32_bf16 v[108:111], v[132:135], v[210:213], v[108:111]
	v_mfma_f32_16x16x32_bf16 v[104:107], v[140:143], v[210:213], v[104:107]
	v_mfma_f32_16x16x32_bf16 v[92:95], v[132:135], v[232:235], v[92:95]
	v_mfma_f32_16x16x32_bf16 v[88:91], v[140:143], v[232:235], v[88:91]
	v_mfma_f32_16x16x32_bf16 v[76:79], v[132:135], v[240:243], v[76:79]
	v_mfma_f32_16x16x32_bf16 v[72:75], v[140:143], v[240:243], v[72:75]
	s_setprio 0
	s_setprio 1
	v_mfma_f32_16x16x32_bf16 v[116:119], v[170:173], v[198:201], v[116:119]
	v_mfma_f32_16x16x32_bf16 v[112:115], v[180:183], v[198:201], v[112:115]
	v_mfma_f32_16x16x32_bf16 v[100:103], v[170:173], v[206:209], v[100:103]
	v_mfma_f32_16x16x32_bf16 v[96:99], v[180:183], v[206:209], v[96:99]
	v_mfma_f32_16x16x32_bf16 v[84:87], v[170:173], v[228:231], v[84:87]
	v_mfma_f32_16x16x32_bf16 v[80:83], v[180:183], v[228:231], v[80:83]
	v_mfma_f32_16x16x32_bf16 v[68:71], v[170:173], v[236:239], v[68:71]
	v_mfma_f32_16x16x32_bf16 v[64:67], v[180:183], v[236:239], v[64:67]
	v_mfma_f32_16x16x32_bf16 v[116:119], v[174:177], v[202:205], v[116:119]
	v_mfma_f32_16x16x32_bf16 v[112:115], v[194:197], v[202:205], v[112:115]
	v_mfma_f32_16x16x32_bf16 v[100:103], v[174:177], v[210:213], v[100:103]
	v_mfma_f32_16x16x32_bf16 v[96:99], v[194:197], v[210:213], v[96:99]
	v_mfma_f32_16x16x32_bf16 v[84:87], v[174:177], v[232:235], v[84:87]
	v_mfma_f32_16x16x32_bf16 v[80:83], v[194:197], v[232:235], v[80:83]
	v_mfma_f32_16x16x32_bf16 v[68:71], v[174:177], v[240:243], v[68:71]
	v_mfma_f32_16x16x32_bf16 v[64:67], v[194:197], v[240:243], v[64:67]
	s_setprio 0
	s_barrier
	s_add_i32 s39, s39, s22
	v_lshl_add_u64 v[214:215], s[2:3], 0, v[148:149]
	s_mov_b32 m0, s39
	ds_read_b128 v[198:201], v179 offset:16384
	ds_read_b128 v[202:205], v179 offset:17408
	ds_read_b128 v[206:209], v179 offset:18432
	ds_read_b128 v[210:213], v179 offset:19456
	ds_read_b128 v[228:231], v179 offset:20480
	ds_read_b128 v[232:235], v179 offset:21504
	ds_read_b128 v[236:239], v179 offset:22528
	ds_read_b128 v[240:243], v179 offset:23552
	global_load_lds_dwordx4 v[214:215], off
	s_add_i32 m0, s39, 0x2000
	s_add_u32 s40, s2, 0x40000
	v_lshl_add_u64 v[224:225], s[2:3], 0, v[144:145]
	s_addc_u32 s41, s3, 0
	s_add_i32 s39, s54, s22
	global_load_lds_dwordx4 v[224:225], off
	v_lshl_add_u64 v[244:245], s[40:41], 0, v[148:149]
	s_mov_b32 m0, s39
	v_lshl_add_u64 v[246:247], s[24:25], 0, v[146:147]
	global_load_lds_dwordx4 v[244:245], off
	v_lshl_add_u64 v[244:245], s[40:41], 0, v[144:145]
	s_add_i32 m0, s39, 0x2000
	s_nop 0
	global_load_lds_dwordx4 v[244:245], off
	v_lshl_add_u64 v[244:245], s[24:25], 0, v[150:151]
	s_mov_b32 m0, s23
	s_nop 0
	global_load_lds_dwordx4 v[244:245], off
	s_mov_b32 m0, s44
	s_nop 0
	global_load_lds_dwordx4 v[246:247], off
	s_waitcnt vmcnt(8)
	s_waitcnt lgkmcnt(0)
	s_barrier
; #define PG8_LAS __attribute__((address_space(3)))
; __device__ __forceinline__ unsigned cvt_pk_bf16(float lo, float hi) { unsigned r; asm volatile("v_cvt_pk_bf16_f32 %0, %1, %2" : "=v"(r) : "v"(lo), "v"(hi)); return r; }
; __device__ __forceinline__ float sum4(const f32x4 a) { return (a[0] + a[1]) + (a[2] + a[3]); }
; #define PG8_STAGE(bufoff, gbase, voff) do { _Pragma("unroll") for (int _i = 0; _i < 2; ++_i) \
;         __builtin_amdgcn_global_load_lds((const unsigned*)((const char*)(gbase) + (voff)[_i]), (PG8_LAS unsigned*)(lds + (bufoff) + ldsw + _i * 8192), 16, 0, 0); } while (0)
; #define PG8_LDA(dst, b, h) do { _Pragma("unroll") for (int m = 0; m < 4; ++m) _Pragma("unroll") for (int k = 0; k < 2; ++k) dst[m][k] = *(const PG8_LAS bf16x8*)(lds + PG8_SA(b, h) + aoff + m * 2048 + k * 1024); } while (0)
; #define PG8_WAIT_V(n) asm volatile("s_waitcnt vmcnt(" #n ")" ::: "memory")
; __device__ __forceinline__ float row_rstd(const float* ps_row) {
;     const f32x4* p = (const f32x4*)ps_row; const f32x4 a = p[0], b = p[1], c = p[2], d = p[3];
;     const float s = (sum4(a) + sum4(b)) + (sum4(c) + sum4(d));
;     return 1.0f / sqrtf(s * (1.0f / 1024.0f) + E_EPS);
; }
; __device__ __forceinline__ u32x4 pack8(const f32x4 a, const f32x4 b) { u32x4 w; w.x = cvt_pk_bf16(a[0], a[1]); w.y = cvt_pk_bf16(a[2], a[3]); w.z = cvt_pk_bf16(b[0], b[1]); w.w = cvt_pk_bf16(b[2], b[3]); return w; }
; __device__ __forceinline__ bf16_t f2bf1(float f) { return (bf16_t)(cvt_pk_bf16(f, 0.f) & 0xffffu); }
; __device__ __forceinline__ PG8_LAS const float* stage_rstd(const float* PS, PG8_LAS unsigned char* lds, int pm) {
;     int t = threadIdx.x; asm volatile("" : "+v"(t));
;     PG8_LAS float* R = (PG8_LAS float*)(lds + 131072);
;     if (t < 256) R[t] = row_rstd(PS + (size_t)(pm * BM + t) * 16);
; template <class Epi, class Sched, bool ALIGN_EPI = false, bool SP2 = false>
; __device__ __forceinline__ void gemm_phase(PG8_LAS unsigned char* lds, const Gemm g, const Sched& S, const Epi& E) {
;     ...
;             PG8_WAIT_V(8); PG8_WAIT_L(0); PG8_BAR; PG8_MMA(0, 0, At, B0); PG8_MMA(0, 1, At, B1); PG8_BAR; PG8_SCHED;
;             PG8_LDA(At, 0, 1); PG8_STAGE(PG8_SB(0, 0), b2, voffB); PG8_STAGE(PG8_SB(0, 1), b2 + hstep, voffB); PG8_STAGE(PG8_SA(0, 0), a2, voffA);
;             PG8_WAIT_V(8); PG8_WAIT_L(0); PG8_BAR; PG8_MMA(1, 0, At, B0); PG8_MMA(1, 1, At, B1); PG8_BAR; PG8_SCHED;
	s_setprio 1
	s_waitcnt lgkmcnt(0)
	v_mfma_f32_16x16x32_bf16 v[60:63], v[128:131], v[198:201], v[60:63]
	v_mfma_f32_16x16x32_bf16 v[56:59], v[136:139], v[198:201], v[56:59]
	v_mfma_f32_16x16x32_bf16 v[44:47], v[128:131], v[206:209], v[44:47]
	v_mfma_f32_16x16x32_bf16 v[40:43], v[136:139], v[206:209], v[40:43]
	v_mfma_f32_16x16x32_bf16 v[28:31], v[128:131], v[228:231], v[28:31]
	v_mfma_f32_16x16x32_bf16 v[24:27], v[136:139], v[228:231], v[24:27]
	v_mfma_f32_16x16x32_bf16 v[12:15], v[128:131], v[236:239], v[12:15]
	v_mfma_f32_16x16x32_bf16 v[8:11], v[136:139], v[236:239], v[8:11]
	v_mfma_f32_16x16x32_bf16 v[60:63], v[132:135], v[202:205], v[60:63]
	v_mfma_f32_16x16x32_bf16 v[56:59], v[140:143], v[202:205], v[56:59]
	v_mfma_f32_16x16x32_bf16 v[44:47], v[132:135], v[210:213], v[44:47]
	v_mfma_f32_16x16x32_bf16 v[40:43], v[140:143], v[210:213], v[40:43]
	v_mfma_f32_16x16x32_bf16 v[28:31], v[132:135], v[232:235], v[28:31]
	v_mfma_f32_16x16x32_bf16 v[24:27], v[140:143], v[232:235], v[24:27]
	v_mfma_f32_16x16x32_bf16 v[12:15], v[132:135], v[240:243], v[12:15]
	v_mfma_f32_16x16x32_bf16 v[8:11], v[140:143], v[240:243], v[8:11]
	s_setprio 0
	s_setprio 1
	v_mfma_f32_16x16x32_bf16 v[52:55], v[170:173], v[198:201], v[52:55]
	v_mfma_f32_16x16x32_bf16 v[48:51], v[180:183], v[198:201], v[48:51]
	v_mfma_f32_16x16x32_bf16 v[36:39], v[170:173], v[206:209], v[36:39]
	v_mfma_f32_16x16x32_bf16 v[32:35], v[180:183], v[206:209], v[32:35]
	v_mfma_f32_16x16x32_bf16 v[20:23], v[170:173], v[228:231], v[20:23]
	v_mfma_f32_16x16x32_bf16 v[16:19], v[180:183], v[228:231], v[16:19]
	v_mfma_f32_16x16x32_bf16 v[4:7], v[170:173], v[236:239], v[4:7]
	v_mfma_f32_16x16x32_bf16 v[0:3], v[180:183], v[236:239], v[0:3]
	v_mfma_f32_16x16x32_bf16 v[52:55], v[174:177], v[202:205], v[52:55]
	v_mfma_f32_16x16x32_bf16 v[48:51], v[194:197], v[202:205], v[48:51]
	v_mfma_f32_16x16x32_bf16 v[36:39], v[174:177], v[210:213], v[36:39]
	v_mfma_f32_16x16x32_bf16 v[32:35], v[194:197], v[210:213], v[32:35]
	v_mfma_f32_16x16x32_bf16 v[20:23], v[174:177], v[232:235], v[20:23]
	v_mfma_f32_16x16x32_bf16 v[16:19], v[194:197], v[232:235], v[16:19]
	v_mfma_f32_16x16x32_bf16 v[4:7], v[174:177], v[240:243], v[4:7]
	v_mfma_f32_16x16x32_bf16 v[0:3], v[194:197], v[240:243], v[0:3]
	s_setprio 0
	s_barrier
	s_add_i32 s39, 0, 0x18000
	s_add_i32 s40, 0, 0x1c000
	s_cmp_eq_u32 s38, 12
	s_cbranch_scc0 .Lrs_in_b
	v_add_f32_e32 v190, v190, v191
	v_add_f32_e32 v226, v226, v227
	v_add_f32_e32 v217, v217, v220
	v_add_f32_e32 v223, v223, v250
	v_add_f32_e32 v190, v190, v226
	v_add_f32_e32 v217, v217, v223
	v_add_f32_e32 v190, v190, v217
	s_nop 1
	v_add_f32_dpp v190, v190, v190 quad_perm:[1,0,3,2] row_mask:0xf bank_mask:0xf
	s_mov_b32 s98, 0xf800000
	v_fmamk_f32 v190, v190, 0x3a800000, v218
	v_mul_f32_e32 v191, 0x4f800000, v190
	v_cmp_gt_f32_e32 vcc, s98, v190
	s_nop 1
	v_cndmask_b32_e32 v190, v190, v191, vcc
	v_sqrt_f32_e32 v191, v190
	s_nop 0
	v_add_u32_e32 v217, -1, v191
	v_add_u32_e32 v220, 1, v191
	v_fma_f32 v223, -v217, v191, v190
	v_fma_f32 v226, -v220, v191, v190
	v_cmp_ge_f32_e64 s[98:99], 0, v223
	s_nop 1
	v_cndmask_b32_e64 v191, v191, v217, s[98:99]
	v_cmp_lt_f32_e64 s[98:99], 0, v226
	s_nop 1
	v_cndmask_b32_e64 v191, v191, v220, s[98:99]
	v_mul_f32_e32 v217, 0x37800000, v191
	v_cndmask_b32_e32 v191, v191, v217, vcc
	v_cmp_class_f32_e32 vcc, v190, v219
	s_nop 1
	v_cndmask_b32_e32 v190, v191, v190, vcc
	v_div_scale_f32 v191, s[98:99], v190, v190, 1.0
	v_rcp_f32_e32 v217, v191
	v_div_scale_f32 v220, vcc, 1.0, v190, 1.0
	v_fma_f32 v223, -v191, v217, 1.0
	v_fmac_f32_e32 v217, v223, v217
	v_mul_f32_e32 v223, v220, v217
	v_fma_f32 v226, -v191, v223, v220
	v_fmac_f32_e32 v223, v226, v217
	v_fma_f32 v191, -v191, v223, v220
	v_div_fmas_f32 v191, v191, v217, v223
	v_div_fixup_f32 v190, v191, v190, 1.0
	v_lshrrev_b32_e32 v250, 1, v216
	v_lshl_add_u32 v250, v250, 2, 0
	v_add_u32_e32 v250, 0x20000, v250
	ds_write_b32 v250, v190
.Lrs_in_b:
	v_add_u32_e32 v140, s39, v155
	v_add_u32_e32 v184, s40, v155
	ds_read_b128 v[128:131], v140
	ds_read_b128 v[132:135], v140 offset:1024
	ds_read_b128 v[136:139], v140 offset:2048
	ds_read_b128 v[140:143], v140 offset:3072
	ds_read_b128 v[170:173], v184
	ds_read_b128 v[174:177], v184 offset:1024
	ds_read_b128 v[180:183], v184 offset:2048
	ds_read_b128 v[194:197], v184 offset:3072
	s_add_u32 s24, s24, 0x40000
	s_addc_u32 s25, s25, 0
	s_mov_b32 m0, s45
	v_lshl_add_u64 v[248:249], s[24:25], 0, v[150:151]
	ds_read_b128 v[198:201], v179 offset:32768
	ds_read_b128 v[202:205], v179 offset:33792
	ds_read_b128 v[206:209], v179 offset:34816
	ds_read_b128 v[210:213], v179 offset:35840
	ds_read_b128 v[228:231], v179 offset:36864
	ds_read_b128 v[232:235], v179 offset:37888
	ds_read_b128 v[236:239], v179 offset:38912
	ds_read_b128 v[240:243], v179 offset:39936
	global_load_lds_dwordx4 v[248:249], off
	v_lshl_add_u64 v[248:249], s[24:25], 0, v[146:147]
	s_mov_b32 m0, s46
	s_nop 0
	global_load_lds_dwordx4 v[248:249], off
	s_waitcnt vmcnt(8)
	s_waitcnt lgkmcnt(0)
	s_barrier
; #define PG8_STAGE(bufoff, gbase, voff) do { _Pragma("unroll") for (int _i = 0; _i < 2; ++_i) \
;         __builtin_amdgcn_global_load_lds((const unsigned*)((const char*)(gbase) + (voff)[_i]), (PG8_LAS unsigned*)(lds + (bufoff) + ldsw + _i * 8192), 16, 0, 0); } while (0)
; #define PG8_LDA(dst, b, h) do { _Pragma("unroll") for (int m = 0; m < 4; ++m) _Pragma("unroll") for (int k = 0; k < 2; ++k) dst[m][k] = *(const PG8_LAS bf16x8*)(lds + PG8_SA(b, h) + aoff + m * 2048 + k * 1024); } while (0)
; #define PG8_LDB(dst, b, h) do { _Pragma("unroll") for (int n = 0; n < 2; ++n) _Pragma("unroll") for (int k = 0; k < 2; ++k) dst[n][k] = *(const PG8_LAS bf16x8*)(lds + PG8_SB(b, h) + boff + n * 2048 + k * 1024); } while (0)
; #define PG8_MMA(ai, bj, At, Bt) do { __builtin_amdgcn_s_setprio(1); _Pragma("unroll") for (int m = 0; m < 4; ++m) _Pragma("unroll") for (int n = 0; n < 2; ++n) _Pragma("unroll") for (int k = 0; k < 2; ++k) \
;         acc[ai][bj][m][n] = __builtin_amdgcn_mfma_f32_16x16x32_bf16(Bt[n][k], At[m][k], acc[ai][bj][m][n], 0, 0, 0); __builtin_amdgcn_s_setprio(0); } while (0)
; #define PG8_WAIT_V(n) asm volatile("s_waitcnt vmcnt(" #n ")" ::: "memory")
; #define PG8_WAIT_L(n) asm volatile("s_waitcnt lgkmcnt(" #n ")" ::: "memory")
; #define PG8_BAR __builtin_amdgcn_s_barrier()
; #define PG8_SCHED __builtin_amdgcn_sched_barrier(0)
; template <class Epi, class Sched, bool ALIGN_EPI = false, bool SP2 = false>
; __device__ __forceinline__ void gemm_phase(PG8_LAS unsigned char* lds, const Gemm g, const Sched& S, const Epi& E) {
;     ...
;             PG8_WAIT_V(8); PG8_WAIT_L(0); PG8_BAR; PG8_MMA(1, 0, At, B0); PG8_MMA(1, 1, At, B1); PG8_BAR; PG8_SCHED;
;             PG8_LDB(B0, 1, 0); PG8_LDB(B1, 1, 1); PG8_SCHED; PG8_LDA(At, 1, 0); PG8_STAGE(PG8_SA(0, 1), a2 + hstep, voffA);
;             PG8_WAIT_V(8); PG8_WAIT_L(0); PG8_BAR; PG8_MMA(0, 0, At, B0); PG8_MMA(0, 1, At, B1); PG8_BAR; PG8_SCHED;
;             PG8_LDA(At, 1, 1); PG8_STAGE(PG8_SB(1, 0), b3, voffB); PG8_STAGE(PG8_SB(1, 1), b3 + hstep, voffB); PG8_STAGE(PG8_SA(1, 0), a3, voffA);
;             PG8_WAIT_V(8); PG8_WAIT_L(0); PG8_BAR; PG8_MMA(1, 0, At, B0); PG8_MMA(1, 1, At, B1); PG8_BAR; PG8_SCHED;
	s_setprio 1
	s_waitcnt lgkmcnt(0)
	v_mfma_f32_16x16x32_bf16 v[124:127], v[128:131], v[198:201], v[124:127]
	v_mfma_f32_16x16x32_bf16 v[120:123], v[136:139], v[198:201], v[120:123]
	v_mfma_f32_16x16x32_bf16 v[108:111], v[128:131], v[206:209], v[108:111]
	v_mfma_f32_16x16x32_bf16 v[104:107], v[136:139], v[206:209], v[104:107]
	v_mfma_f32_16x16x32_bf16 v[92:95], v[128:131], v[228:231], v[92:95]
	v_mfma_f32_16x16x32_bf16 v[88:91], v[136:139], v[228:231], v[88:91]
	v_mfma_f32_16x16x32_bf16 v[76:79], v[128:131], v[236:239], v[76:79]
	v_mfma_f32_16x16x32_bf16 v[72:75], v[136:139], v[236:239], v[72:75]
	v_mfma_f32_16x16x32_bf16 v[124:127], v[132:135], v[202:205], v[124:127]
	v_mfma_f32_16x16x32_bf16 v[120:123], v[140:143], v[202:205], v[120:123]
	v_mfma_f32_16x16x32_bf16 v[108:111], v[132:135], v[210:213], v[108:111]
	v_mfma_f32_16x16x32_bf16 v[104:107], v[140:143], v[210:213], v[104:107]
	v_mfma_f32_16x16x32_bf16 v[92:95], v[132:135], v[232:235], v[92:95]
	v_mfma_f32_16x16x32_bf16 v[88:91], v[140:143], v[232:235], v[88:91]
	v_mfma_f32_16x16x32_bf16 v[76:79], v[132:135], v[240:243], v[76:79]
	v_mfma_f32_16x16x32_bf16 v[72:75], v[140:143], v[240:243], v[72:75]
	s_setprio 0
	s_setprio 1
	v_mfma_f32_16x16x32_bf16 v[116:119], v[170:173], v[198:201], v[116:119]
	v_mfma_f32_16x16x32_bf16 v[112:115], v[180:183], v[198:201], v[112:115]
	v_mfma_f32_16x16x32_bf16 v[100:103], v[170:173], v[206:209], v[100:103]
	v_mfma_f32_16x16x32_bf16 v[96:99], v[180:183], v[206:209], v[96:99]
	v_mfma_f32_16x16x32_bf16 v[84:87], v[170:173], v[228:231], v[84:87]
	v_mfma_f32_16x16x32_bf16 v[80:83], v[180:183], v[228:231], v[80:83]
	v_mfma_f32_16x16x32_bf16 v[68:71], v[170:173], v[236:239], v[68:71]
	v_mfma_f32_16x16x32_bf16 v[64:67], v[180:183], v[236:239], v[64:67]
	v_mfma_f32_16x16x32_bf16 v[116:119], v[174:177], v[202:205], v[116:119]
	v_mfma_f32_16x16x32_bf16 v[112:115], v[194:197], v[202:205], v[112:115]
	v_mfma_f32_16x16x32_bf16 v[100:103], v[174:177], v[210:213], v[100:103]
	v_mfma_f32_16x16x32_bf16 v[96:99], v[194:197], v[210:213], v[96:99]
	v_mfma_f32_16x16x32_bf16 v[84:87], v[174:177], v[232:235], v[84:87]
	v_mfma_f32_16x16x32_bf16 v[80:83], v[194:197], v[232:235], v[80:83]
	v_mfma_f32_16x16x32_bf16 v[68:71], v[174:177], v[240:243], v[68:71]
	v_mfma_f32_16x16x32_bf16 v[64:67], v[194:197], v[240:243], v[64:67]
	s_setprio 0
	s_barrier
	s_add_i32 s24, s39, s22
	v_lshl_add_u64 v[214:215], v[214:215], 0, s[96:97]
	s_mov_b32 m0, s24
	ds_read_b128 v[198:201], v179 offset:49152
	ds_read_b128 v[202:205], v179 offset:50176
	ds_read_b128 v[206:209], v179 offset:51200
	ds_read_b128 v[210:213], v179 offset:52224
	ds_read_b128 v[228:231], v179 offset:53248
	ds_read_b128 v[232:235], v179 offset:54272
	ds_read_b128 v[236:239], v179 offset:55296
	ds_read_b128 v[240:243], v179 offset:56320
	global_load_lds_dwordx4 v[214:215], off
	s_add_i32 m0, s24, 0x2000
	s_add_u32 s2, s2, 0x40080
	v_lshl_add_u64 v[214:215], v[224:225], 0, s[96:97]
	s_addc_u32 s3, s3, 0
	s_add_i32 s24, s40, s22
	global_load_lds_dwordx4 v[214:215], off
	v_lshl_add_u64 v[214:215], s[2:3], 0, v[148:149]
	s_mov_b32 m0, s24
	s_nop 0
	global_load_lds_dwordx4 v[214:215], off
	v_lshl_add_u64 v[214:215], s[2:3], 0, v[144:145]
	s_add_i32 m0, s24, 0x2000
	s_nop 0
	global_load_lds_dwordx4 v[214:215], off
	v_lshl_add_u64 v[214:215], v[244:245], 0, s[96:97]
	s_mov_b32 m0, s47
	s_nop 0
	global_load_lds_dwordx4 v[214:215], off
	v_lshl_add_u64 v[214:215], v[246:247], 0, s[96:97]
	s_mov_b32 m0, s48
	s_nop 0
	global_load_lds_dwordx4 v[214:215], off
	s_waitcnt vmcnt(8)
	s_waitcnt lgkmcnt(0)
	s_barrier
	s_setprio 1
	s_waitcnt lgkmcnt(0)
	v_mfma_f32_16x16x32_bf16 v[60:63], v[128:131], v[198:201], v[60:63]
	v_mfma_f32_16x16x32_bf16 v[56:59], v[136:139], v[198:201], v[56:59]
	v_mfma_f32_16x16x32_bf16 v[44:47], v[128:131], v[206:209], v[44:47]
	v_mfma_f32_16x16x32_bf16 v[40:43], v[136:139], v[206:209], v[40:43]
	v_mfma_f32_16x16x32_bf16 v[28:31], v[128:131], v[228:231], v[28:31]
	v_mfma_f32_16x16x32_bf16 v[24:27], v[136:139], v[228:231], v[24:27]
	v_mfma_f32_16x16x32_bf16 v[12:15], v[128:131], v[236:239], v[12:15]
	v_mfma_f32_16x16x32_bf16 v[8:11], v[136:139], v[236:239], v[8:11]
	v_mfma_f32_16x16x32_bf16 v[60:63], v[132:135], v[202:205], v[60:63]
	v_mfma_f32_16x16x32_bf16 v[56:59], v[140:143], v[202:205], v[56:59]
	v_mfma_f32_16x16x32_bf16 v[44:47], v[132:135], v[210:213], v[44:47]
	v_mfma_f32_16x16x32_bf16 v[40:43], v[140:143], v[210:213], v[40:43]
	v_mfma_f32_16x16x32_bf16 v[28:31], v[132:135], v[232:235], v[28:31]
	v_mfma_f32_16x16x32_bf16 v[24:27], v[140:143], v[232:235], v[24:27]
	v_mfma_f32_16x16x32_bf16 v[12:15], v[132:135], v[240:243], v[12:15]
	v_mfma_f32_16x16x32_bf16 v[8:11], v[140:143], v[240:243], v[8:11]
	s_setprio 0
	s_setprio 1
	v_mfma_f32_16x16x32_bf16 v[52:55], v[170:173], v[198:201], v[52:55]
	v_mfma_f32_16x16x32_bf16 v[48:51], v[180:183], v[198:201], v[48:51]
	v_mfma_f32_16x16x32_bf16 v[36:39], v[170:173], v[206:209], v[36:39]
	v_mfma_f32_16x16x32_bf16 v[32:35], v[180:183], v[206:209], v[32:35]
	v_mfma_f32_16x16x32_bf16 v[20:23], v[170:173], v[228:231], v[20:23]
	v_mfma_f32_16x16x32_bf16 v[16:19], v[180:183], v[228:231], v[16:19]
	v_mfma_f32_16x16x32_bf16 v[4:7], v[170:173], v[236:239], v[4:7]
	v_mfma_f32_16x16x32_bf16 v[0:3], v[180:183], v[236:239], v[0:3]
	v_mfma_f32_16x16x32_bf16 v[52:55], v[174:177], v[202:205], v[52:55]
	v_mfma_f32_16x16x32_bf16 v[48:51], v[194:197], v[202:205], v[48:51]
	v_mfma_f32_16x16x32_bf16 v[36:39], v[174:177], v[210:213], v[36:39]
	v_mfma_f32_16x16x32_bf16 v[32:35], v[194:197], v[210:213], v[32:35]
	v_mfma_f32_16x16x32_bf16 v[20:23], v[174:177], v[232:235], v[20:23]
	v_mfma_f32_16x16x32_bf16 v[16:19], v[194:197], v[232:235], v[16:19]
	v_mfma_f32_16x16x32_bf16 v[4:7], v[174:177], v[240:243], v[4:7]
	v_mfma_f32_16x16x32_bf16 v[0:3], v[194:197], v[240:243], v[0:3]
	s_setprio 0
	s_barrier
	s_add_i32 s38, s38, 2
	s_add_u32 s0, s0, 0x100
	s_addc_u32 s1, s1, 0
	s_add_u32 s11, s11, 0x100
	s_addc_u32 s19, s19, 0
	s_cmp_gt_u32 s38, 13
	s_cbranch_scc0 .LBB0_533
	s_and_b64 vcc, exec, s[14:15]
	s_cbranch_vccz .LBB0_536
	s_barrier
; #define PG8_LAS __attribute__((address_space(3)))
; __device__ __forceinline__ u32x4 pack8(const f32x4 a, const f32x4 b) { u32x4 w; w.x = cvt_pk_bf16(a[0], a[1]); w.y = cvt_pk_bf16(a[2], a[3]); w.z = cvt_pk_bf16(b[0], b[1]); w.w = cvt_pk_bf16(b[2], b[3]); return w; }
;     __device__ __forceinline__ void operator()(const f32x4 (&acc)[2][2][4][2], const Unit& u, int wr, int wc, int fr, int fq) const {
;     ...
;         PG8_LAS const float* R = stage_rstd((const float*)(ws + WS_PS), lds, u.pm);
;         const bool is_s = (u.pm >= 64);
;         if (pn <= 1 || pn == 6 || (pn == 2 && wc < 2)) {
;     ...
;         } else {
;             float* ocp = out + O_CVP + (size_t)l * 4096; float* ocs = out + O_CVS + (size_t)l * 16384;
; #pragma unroll
;             for (int ai = 0; ai < 2; ++ai)
; #pragma unroll
;                 for (int m = 0; m < 4; ++m) {
;                     int row = u.pm * BM + ai * HALF + wr * 64 + m * 16 + fr;
;                     asm volatile("" : "+v"(row));
;                     const float rs = R[ai * HALF + wr * 64 + m * 16 + fr];
;                     const float rs2 = rs * rs;
;                     const f32x4 p0 = acc[ai][0][m][0] * acc[ai][1][m][0] * rs2, p1 = acc[ai][0][m][1] * acc[ai][1][m][1] * rs2;
;                     const int ch0 = (pn - 4) * 128 + wc * 32 + 8 * fq;
;                     *(u32x4*)(UB + (size_t)row * E_UBW + 896 + ch0) = pack8(p0, p1);
;                     const int sb = (row - E_MP) >> 6, st = (row - E_MP) & 63, pb = row >> 11, pt = row & 2047;
;                     if (is_s) { if (st >= 62) { float* d = ocs + ((size_t)(sb * 2 + (st - 62)) * 256 + ch0); __builtin_nontemporal_store(p0, (f32x4*)d); __builtin_nontemporal_store(p1, (f32x4*)(d + 4)); } }
;                     else if (pt >= 2046) { float* d = ocp + ((size_t)(pb * 2 + (pt - 2046)) * 256 + ch0); __builtin_nontemporal_store(p0, (f32x4*)d); __builtin_nontemporal_store(p1, (f32x4*)(d + 4)); }
.LBB0_536:
.LBB0_538:
	s_cmp_gt_i32 s53, 63
	s_cselect_b64 s[38:39], -1, 0
	s_cmp_lt_i32 s53, 64
	s_cselect_b64 s[40:41], -1, 0
	s_cmp_lt_i32 s34, 2
	s_cselect_b64 s[24:25], -1, 0
	s_cmp_eq_u32 s34, 6
	s_cselect_b64 s[2:3], -1, 0
	s_or_b64 s[0:1], s[24:25], s[2:3]
	s_and_b64 vcc, exec, s[0:1]
	s_cbranch_vccnz .LBB0_661
	s_cmp_lg_u32 s34, 2
	s_cselect_b64 s[4:5], -1, 0
	s_cmp_eq_u32 s34, 2
	v_readlane_b32 s6, v255, 21
	s_cselect_b64 s[0:1], -1, 0
	v_readlane_b32 s7, v255, 22
	s_and_b64 s[0:1], s[0:1], s[6:7]
	s_andn2_b64 vcc, exec, s[0:1]
	s_mov_b64 s[0:1], -1
	s_cbranch_vccz .LBB0_661
	s_and_b64 vcc, exec, s[4:5]
	s_cbranch_vccz .LBB0_626
	s_cmp_lg_u32 s34, 3
	v_lshl_add_u32 v138, s53, 8, v153
	s_cbranch_scc0 .LBB0_623
	v_mov_b32_e32 v137, v138
	ds_read_b32 v130, v165
	v_pk_mul_f32 v[128:129], v[126:127], v[118:119]
	v_pk_mul_f32 v[132:133], v[124:125], v[116:117]
	v_mov_b64_e32 v[170:171], s[20:21]
	s_movk_i32 s0, 0xb00
	s_waitcnt lgkmcnt(0)
	v_mul_f32_e32 v136, v130, v130
	v_lshl_add_u32 v184, s34, 7, v178
	v_pk_mul_f32 v[130:131], v[128:129], v[136:137] op_sel_hi:[1,0]
	v_pk_mul_f32 v[128:129], v[132:133], v[136:137] op_sel_hi:[1,0]
	v_pk_mul_f32 v[132:133], v[122:123], v[114:115]
	v_pk_mul_f32 v[140:141], v[120:121], v[112:113]
	v_mad_i64_i32 v[170:171], s[0:1], v137, s0, v[170:171]
	v_pk_mul_f32 v[134:135], v[132:133], v[136:137] op_sel_hi:[1,0]
	v_pk_mul_f32 v[132:133], v[140:141], v[136:137] op_sel_hi:[1,0]
	v_lshl_add_u64 v[170:171], v[184:185], 1, v[170:171]
	s_and_b64 vcc, exec, s[40:41]
	v_cvt_pk_bf16_f32 v140, v128, v129
	v_cvt_pk_bf16_f32 v141, v130, v131
	v_cvt_pk_bf16_f32 v142, v132, v133
	v_cvt_pk_bf16_f32 v143, v134, v135
	global_store_dwordx4 v[170:171], v[140:143], off offset:1792
	s_cbranch_vccz .LBB0_547
	v_and_b32_e32 v139, 0x7ff, v137
	s_movk_i32 s0, 0x7fd
	v_cmp_lt_u32_e32 vcc, s0, v139
	s_mov_b64 s[4:5], 0
	s_mov_b64 s[0:1], 0
	s_and_saveexec_b64 s[6:7], vcc
	s_xor_b64 vcc, exec, s[6:7]
	v_ashrrev_i32_e32 v136, 10, v137
	v_and_b32_e32 v136, -2, v136
	s_movk_i32 s6, 0xf802
	s_mov_b64 s[0:1], exec
	v_add3_u32 v136, v139, v136, s6
	s_or_b64 exec, exec, vcc
	s_and_b64 vcc, exec, s[4:5]
	s_cbranch_vccnz .LBB0_548
